# baseline (speedup 1.0000x reference)
; template <bool ROWRMS>
; __device__ __forceinline__ void gemm_mainloop(const u16* __restrict__ A, int lda, const u16* __restrict__ Bt, int ldb,
;                                               int K, f32x16 (&acc)[2][2], char* smem, float* rs) {
;     ...
; #pragma unroll
;     for (int kh = 0; kh < 2; ++kh) {
;       bf16x8 af[2][2], bfr[2][2];
; #pragma unroll
;       for (int ks = 0; ks < 2; ++ks) {
; #pragma unroll
;         for (int i = 0; i < 2; ++i) af[ks][i] = *(const bf16x8*)(As + aofs + i * 32 * 72 + (kh * 2 + ks) * 16);
; #pragma unroll
;         for (int j = 0; j < 2; ++j) bfr[ks][j] = *(const bf16x8*)(Bs + bofs + j * 32 * 72 + (kh * 2 + ks) * 16);
;       }
; #pragma unroll
;       for (int ks = 0; ks < 2; ++ks)
; #pragma unroll
;         for (int i = 0; i < 2; ++i)
; #pragma unroll
;           for (int j = 0; j < 2; ++j)
;             acc[i][j] = __builtin_amdgcn_mfma_f32_32x32x16_bf16(af[ks][i], bfr[ks][j], acc[i][j], 0, 0, 0);
;     }
.LBB0_2266:
	ds_read_b128 v[188:191], v136
	ds_read_b128 v[228:231], v137 offset:18432
	ds_read_b128 v[232:235], v137 offset:23040
	ds_read_b128 v[192:195], v136 offset:4608
	ds_read_b128 v[200:203], v136 offset:32
	ds_read_b128 v[236:239], v137 offset:18464
	ds_read_b128 v[240:243], v137 offset:23072
	ds_read_b128 v[204:207], v136 offset:4640
	s_waitcnt lgkmcnt(6)
	v_mfma_f32_32x32x16_bf16 v[48:63], v[188:191], v[228:231], v[48:63]
	s_waitcnt lgkmcnt(5)
	v_mfma_f32_32x32x16_bf16 v[32:47], v[188:191], v[232:235], v[32:47]
	s_waitcnt lgkmcnt(4)
	v_mfma_f32_32x32x16_bf16 v[16:31], v[192:195], v[228:231], v[16:31]
	v_mfma_f32_32x32x16_bf16 v[0:15], v[192:195], v[232:235], v[0:15]
	ds_read_b128 v[188:191], v136 offset:64
	ds_read_b128 v[228:231], v137 offset:18496
	ds_read_b128 v[232:235], v137 offset:23104
	ds_read_b128 v[192:195], v136 offset:4672
	s_waitcnt lgkmcnt(6)
	v_mfma_f32_32x32x16_bf16 v[48:63], v[200:203], v[236:239], v[48:63]
	s_waitcnt lgkmcnt(5)
	v_mfma_f32_32x32x16_bf16 v[32:47], v[200:203], v[240:243], v[32:47]
	s_waitcnt lgkmcnt(4)
	v_mfma_f32_32x32x16_bf16 v[16:31], v[204:207], v[236:239], v[16:31]
	v_mfma_f32_32x32x16_bf16 v[0:15], v[204:207], v[240:243], v[0:15]
	ds_read_b128 v[200:203], v136 offset:96
	ds_read_b128 v[236:239], v137 offset:18528
	ds_read_b128 v[240:243], v137 offset:23136
	ds_read_b128 v[204:207], v136 offset:4704
	s_waitcnt lgkmcnt(6)
	v_mfma_f32_32x32x16_bf16 v[48:63], v[188:191], v[228:231], v[48:63]
	s_waitcnt lgkmcnt(5)
	v_mfma_f32_32x32x16_bf16 v[32:47], v[188:191], v[232:235], v[32:47]
	s_waitcnt lgkmcnt(4)
	v_mfma_f32_32x32x16_bf16 v[16:31], v[192:195], v[228:231], v[16:31]
	v_mfma_f32_32x32x16_bf16 v[0:15], v[192:195], v[232:235], v[0:15]
	s_waitcnt lgkmcnt(2)
	v_mfma_f32_32x32x16_bf16 v[48:63], v[200:203], v[236:239], v[48:63]
	s_waitcnt lgkmcnt(1)
	v_mfma_f32_32x32x16_bf16 v[32:47], v[200:203], v[240:243], v[32:47]
	s_waitcnt lgkmcnt(0)
	v_mfma_f32_32x32x16_bf16 v[16:31], v[204:207], v[236:239], v[16:31]
	v_mfma_f32_32x32x16_bf16 v[0:15], v[204:207], v[240:243], v[0:15]
	v_lshl_add_u64 v[138:139], v[138:139], 0, s[8:9]
	s_andn2_b64 vcc, exec, s[12:13]
	v_lshl_add_u64 v[134:135], v[134:135], 0, s[8:9]
	s_cbranch_vccz .LBB0_2272

; template <bool ROWRMS>
; __device__ __forceinline__ void gemm_mainloop(const u16* __restrict__ A, int lda, const u16* __restrict__ Bt, int ldb,
;                                               int K, f32x16 (&acc)[2][2], char* smem, float* rs) {
;     ...
;   auto step = [&](GRegs& R, int kt) {
;     __syncthreads();
; #pragma unroll
;     for (int i = 0; i < 4; ++i) {
;       *(u32x4*)(As + wofs + i * 32 * 72) = R.a[i];
;       *(u32x4*)(Bs + wofs + i * 32 * 72) = R.b[i];
;     }
;     if (ROWRMS) {
; #pragma unroll
;       for (int i = 0; i < 4; ++i) {
;         unsigned a[4] = {R.a[i].x, R.a[i].y, R.a[i].z, R.a[i].w};
; #pragma unroll
;         for (int e = 0; e < 4; ++e) {
;           float lo = __uint_as_float(a[e] << 16), hi = __uint_as_float(a[e] & 0xffff0000u);
;           ss[i] += lo * lo + hi * hi;
;         }
;       }
;     }
;     __syncthreads();
;     if (kt + 2 < nk) gl(R, kt + 2);
;     __builtin_amdgcn_sched_barrier(0);
; #pragma unroll
;     for (int kh = 0; kh < 2; ++kh) {
;       bf16x8 af[2][2], bfr[2][2];
; #pragma unroll
;       for (int ks = 0; ks < 2; ++ks) {
; #pragma unroll
;         for (int i = 0; i < 2; ++i) af[ks][i] = *(const bf16x8*)(As + aofs + i * 32 * 72 + (kh * 2 + ks) * 16);
; #pragma unroll
;         for (int j = 0; j < 2; ++j) bfr[ks][j] = *(const bf16x8*)(Bs + bofs + j * 32 * 72 + (kh * 2 + ks) * 16);
;       }
; #pragma unroll
;       for (int ks = 0; ks < 2; ++ks)
; #pragma unroll
;         for (int i = 0; i < 2; ++i)
; #pragma unroll
;           for (int j = 0; j < 2; ++j)
;             acc[i][j] = __builtin_amdgcn_mfma_f32_32x32x16_bf16(af[ks][i], bfr[ks][j], acc[i][j], 0, 0, 0);
;     }
.LBB0_2269:
	ds_read_b128 v[188:191], v136
	ds_read_b128 v[228:231], v137 offset:18432
	ds_read_b128 v[232:235], v137 offset:23040
	ds_read_b128 v[192:195], v136 offset:4608
	ds_read_b128 v[200:203], v136 offset:32
	ds_read_b128 v[236:239], v137 offset:18464
	ds_read_b128 v[240:243], v137 offset:23072
	ds_read_b128 v[204:207], v136 offset:4640
	s_waitcnt lgkmcnt(6)
	v_mfma_f32_32x32x16_bf16 v[48:63], v[188:191], v[228:231], v[48:63]
	s_waitcnt lgkmcnt(5)
	v_mfma_f32_32x32x16_bf16 v[32:47], v[188:191], v[232:235], v[32:47]
	s_waitcnt lgkmcnt(4)
	v_mfma_f32_32x32x16_bf16 v[16:31], v[192:195], v[228:231], v[16:31]
	v_mfma_f32_32x32x16_bf16 v[0:15], v[192:195], v[232:235], v[0:15]
	ds_read_b128 v[188:191], v136 offset:64
	ds_read_b128 v[228:231], v137 offset:18496
	ds_read_b128 v[232:235], v137 offset:23104
	ds_read_b128 v[192:195], v136 offset:4672
	s_waitcnt lgkmcnt(6)
	v_mfma_f32_32x32x16_bf16 v[48:63], v[200:203], v[236:239], v[48:63]
	s_waitcnt lgkmcnt(5)
	v_mfma_f32_32x32x16_bf16 v[32:47], v[200:203], v[240:243], v[32:47]
	s_waitcnt lgkmcnt(4)
	v_mfma_f32_32x32x16_bf16 v[16:31], v[204:207], v[236:239], v[16:31]
	v_mfma_f32_32x32x16_bf16 v[0:15], v[204:207], v[240:243], v[0:15]
	ds_read_b128 v[200:203], v136 offset:96
	ds_read_b128 v[236:239], v137 offset:18528
	ds_read_b128 v[240:243], v137 offset:23136
	ds_read_b128 v[204:207], v136 offset:4704
	s_waitcnt lgkmcnt(6)
	v_mfma_f32_32x32x16_bf16 v[48:63], v[188:191], v[228:231], v[48:63]
	s_waitcnt lgkmcnt(5)
	v_mfma_f32_32x32x16_bf16 v[32:47], v[188:191], v[232:235], v[32:47]
	s_waitcnt lgkmcnt(4)
	v_mfma_f32_32x32x16_bf16 v[16:31], v[192:195], v[228:231], v[16:31]
	v_mfma_f32_32x32x16_bf16 v[0:15], v[192:195], v[232:235], v[0:15]
	s_waitcnt lgkmcnt(2)
	v_mfma_f32_32x32x16_bf16 v[48:63], v[200:203], v[236:239], v[48:63]
	s_waitcnt lgkmcnt(1)
	v_mfma_f32_32x32x16_bf16 v[32:47], v[200:203], v[240:243], v[32:47]
	s_waitcnt lgkmcnt(0)
	v_mfma_f32_32x32x16_bf16 v[16:31], v[204:207], v[236:239], v[16:31]
	v_mfma_f32_32x32x16_bf16 v[0:15], v[204:207], v[240:243], v[0:15]
	s_cmp_gt_u32 s11, 12
	s_barrier
	ds_write_b128 v67, v[68:71]
	ds_write_b128 v67, v[72:75] offset:18432
	ds_write_b128 v67, v[84:87] offset:4608
	ds_write_b128 v67, v[92:95] offset:23040
	ds_write_b128 v67, v[100:103] offset:9216
	ds_write_b128 v67, v[108:111] offset:27648
	ds_write_b128 v67, v[120:123] offset:13824
	ds_write_b128 v67, v[116:119] offset:32256
	s_waitcnt lgkmcnt(0)
	s_barrier
	s_cbranch_scc1 .LBB0_2266
	v_add_co_u32_e32 v72, vcc, 0x200000, v140
	global_load_dwordx4 v[68:71], v[142:143], off offset:384
	s_nop 0
	v_addc_co_u32_e32 v73, vcc, 0, v141, vcc
	v_add_co_u32_e32 v84, vcc, 0x10000, v142
	global_load_dwordx4 v[72:75], v[72:73], off offset:384
	s_nop 0
	v_addc_co_u32_e32 v85, vcc, 0, v143, vcc
	v_add_co_u32_e32 v92, vcc, 0x210000, v140
	global_load_dwordx4 v[84:87], v[84:85], off offset:384
	s_nop 0
	v_addc_co_u32_e32 v93, vcc, 0, v141, vcc
	v_add_co_u32_e32 v100, vcc, 0x20000, v142
	global_load_dwordx4 v[92:95], v[92:93], off offset:384
	s_nop 0
	v_addc_co_u32_e32 v101, vcc, 0, v143, vcc
	v_add_co_u32_e32 v108, vcc, 0x220000, v140
	global_load_dwordx4 v[100:103], v[100:101], off offset:384
	s_nop 0
	v_addc_co_u32_e32 v109, vcc, 0, v141, vcc
	v_add_co_u32_e32 v116, vcc, 0x30000, v142
	global_load_dwordx4 v[108:111], v[108:109], off offset:384
	s_nop 0
	v_addc_co_u32_e32 v117, vcc, 0, v143, vcc
	global_load_dwordx4 v[120:123], v[116:117], off offset:384
	v_add_co_u32_e32 v116, vcc, 0x230000, v140
	s_nop 1
	v_addc_co_u32_e32 v117, vcc, 0, v141, vcc
	global_load_dwordx4 v[116:119], v[116:117], off offset:384
	s_branch .LBB0_2266
